# adds batched layer-1 LoRA weight preparation in phase 8 (23 loads issued before the first wait instead of 11 serial wait-per-access loops) on top of the previous stack
# baseline (speedup 1.0000x reference)
; __device__ __forceinline__ unsigned pk2(float lo, float hi) { return pg8::cvt_pk_bf16(lo, hi); }
; __device__ __forceinline__ void zero_rows(bf16_t* WT, int row0, int nrows, int gt, int NT) { for (int idx = gt; idx < nrows * 2048; idx += NT) WT[(size_t)row0 * 2048 + idx] = 0; }
; __device__ __forceinline__ void transpose_pad(const float* W, int K, int N, bf16_t* WT, int Kp, int Np, int gt, int NT) {
;     for (int idx = gt; idx < Np * Kp; idx += NT) { const int n = idx / Kp, k = idx - n * Kp; const float v = (n < N && k < K) ? W[(size_t)k * N + n] : 0.f; WT[idx] = (bf16_t)(pk2(v, 0.f) & 0xffffu); }
; }
; __device__ __forceinline__ void transpose_mix(const float* W, int N, bf16_t* WT, int row0, const float* mix, bool om, int gt, int NT) {
;     for (int idx = gt; idx < N * 2048; idx += NT) { const int n = idx >> 11, k = idx & 2047; const float mv = mix[k]; const float v = W[(size_t)k * N + n] * (om ? 1.f - mv : mv);
;         WT[(size_t)(row0 + n) * 2048 + k] = (bf16_t)(pk2(v, 0.f) & 0xffffu); }
; }
; __global__ void __launch_bounds__(512, 2) fwd_megakernel(Args a) {
;     ...
;             { const float* mix = ap->in[13]; bf16_t* wld = WSB(WS_WLD1);
;               transpose_mix(ap->in[19], 96, wld, 0, mix + 1 * DM, true, gt, NT); transpose_mix(ap->in[19], 96, wld, 96, mix + 1 * DM, false, gt, NT); zero_rows(wld, 192, 64, gt, NT);
;               transpose_mix(ap->in[22], 96, wld, 256, mix + 4 * DM, true, gt, NT); transpose_mix(ap->in[22], 96, wld, 352, mix + 4 * DM, false, gt, NT); zero_rows(wld, 448, 64, gt, NT);
;               transpose_mix(ap->in[24], 256, wld, 512, mix + 5 * DM, true, gt, NT); transpose_mix(ap->in[24], 256, wld, 768, mix + 5 * DM, false, gt, NT); }
;             transpose_pad(ap->in[20], 96, 2048, WSB(WS_WLU1X), 256, 2048, gt, NT);
;             transpose_pad(ap->in[23], 96, 2048, WSB(WS_WLU1X) + (size_t)2048 * 256, 256, 2048, gt, NT);
;             transpose_pad(ap->in[25], 256, 2048, WSB(WS_WLU1X) + (size_t)2 * 2048 * 256, 256, 2048, gt, NT);
.LBB0_371:
	s_load_dwordx2 s[8:9], s[64:65], 0x68
	s_waitcnt vmcnt(0)
	s_cmp_eq_u32 s48, 0x20000
	s_cbranch_scc0 .Lwp_orig
	s_load_dwordx2 s[18:19], s[64:65], 0x98
	s_load_dwordx2 s[30:31], s[64:65], 0xb0
	s_load_dwordx2 s[34:35], s[64:65], 0xc0
	v_lshl_add_u32 v0, s23, 9, v43
	v_and_b32_e32 v1, 0x7ff, v0
	v_lshrrev_b32_e32 v2, 11, v0
	v_lshlrev_b32_e32 v3, 2, v1
	v_add_u32_e32 v4, 0x2000, v3
	v_add_u32_e32 v5, 0x8000, v3
	v_add_u32_e32 v6, 0xa000, v3
	v_mul_u32_u24_e32 v7, 0x60, v1
	v_add_lshl_u32 v7, v7, v2, 2
	v_lshl_add_u32 v8, v1, 8, v2
	v_lshlrev_b32_e32 v8, 2, v8
	v_mov_b32_e32 v14, 0
	v_mov_b32_e32 v16, 0
	s_waitcnt lgkmcnt(0)
	global_load_dword v10, v4, s[8:9]
	global_load_dword v11, v5, s[8:9]
	global_load_dword v12, v6, s[8:9]
	global_load_dword v13, v7, s[18:19]
	global_load_dword v15, v7, s[30:31]
	global_load_dword v17, v8, s[34:35]
	global_load_dword v18, v8, s[34:35] offset:256
	global_load_dword v19, v8, s[34:35] offset:512
	global_load_dword v20, v8, s[34:35] offset:768
	v_cmp_gt_u32_e32 vcc, 32, v2
	s_and_saveexec_b64 s[42:43], vcc
	global_load_dword v14, v7, s[18:19] offset:256
	global_load_dword v16, v7, s[30:31] offset:256
	s_or_b64 exec, exec, s[42:43]
	s_load_dwordx2 s[18:19], s[64:65], 0xa0
	s_load_dwordx2 s[30:31], s[64:65], 0xb8
	s_load_dwordx2 s[34:35], s[64:65], 0xc8
	v_and_b32_e32 v21, 0xff, v0
	v_lshrrev_b32_e32 v22, 8, v0
	v_lshl_add_u32 v23, v21, 11, v22
	v_lshlrev_b32_e32 v23, 2, v23
	v_add_u32_e32 v24, 0x1000, v23
	v_mov_b32_e32 v25, 0
	v_mov_b32_e32 v26, 0
	v_mov_b32_e32 v27, 0
	v_mov_b32_e32 v28, 0
	v_mov_b32_e32 v29, 0
	v_mov_b32_e32 v30, 0
	v_mov_b32_e32 v31, 0
	v_mov_b32_e32 v32, 0
	s_waitcnt lgkmcnt(0)
	global_load_dword v33, v23, s[34:35]
	global_load_dword v34, v23, s[34:35] offset:2048
	global_load_dword v35, v24, s[34:35]
	global_load_dword v36, v24, s[34:35] offset:2048
	v_cmp_gt_u32_e32 vcc, 0x60, v21
	s_and_saveexec_b64 s[42:43], vcc
	global_load_dword v25, v23, s[18:19]
	global_load_dword v26, v23, s[18:19] offset:2048
	global_load_dword v27, v24, s[18:19]
	global_load_dword v28, v24, s[18:19] offset:2048
	global_load_dword v29, v23, s[30:31]
	global_load_dword v30, v23, s[30:31] offset:2048
	global_load_dword v31, v24, s[30:31]
	global_load_dword v32, v24, s[30:31] offset:2048
	s_or_b64 exec, exec, s[42:43]
	v_lshlrev_b32_e32 v37, 12, v2
	v_lshl_add_u32 v37, v1, 1, v37
	v_lshlrev_b32_e32 v38, 1, v0
	s_waitcnt vmcnt(0)
	v_sub_f32_e32 v9, 1.0, v10
	v_sub_f32_e32 v39, 1.0, v11
	v_sub_f32_e32 v40, 1.0, v12
	v_mul_f32_e32 v41, v13, v9
	v_cvt_pk_bf16_f32 v41, v41, v129
	v_add_u32_e32 v3, 0x0, v37
	global_store_short v3, v41, s[38:39]
	v_mul_f32_e32 v41, v10, v13
	v_cvt_pk_bf16_f32 v41, v41, v129
	v_add_u32_e32 v3, 0x60000, v37
	global_store_short v3, v41, s[38:39]
	v_mul_f32_e32 v41, v15, v39
	v_cvt_pk_bf16_f32 v41, v41, v129
	v_add_u32_e32 v3, 0x100000, v37
	global_store_short v3, v41, s[38:39]
	v_mul_f32_e32 v41, v11, v15
	v_cvt_pk_bf16_f32 v41, v41, v129
	v_add_u32_e32 v3, 0x160000, v37
	global_store_short v3, v41, s[38:39]
	v_mul_f32_e32 v41, v17, v40
	v_cvt_pk_bf16_f32 v41, v41, v129
	v_add_u32_e32 v3, 0x200000, v37
	global_store_short v3, v41, s[38:39]
	v_mul_f32_e32 v41, v12, v17
	v_cvt_pk_bf16_f32 v41, v41, v129
	v_add_u32_e32 v3, 0x300000, v37
	global_store_short v3, v41, s[38:39]
	v_mul_f32_e32 v41, v18, v40
	v_cvt_pk_bf16_f32 v41, v41, v129
	v_add_u32_e32 v3, 0x240000, v37
	global_store_short v3, v41, s[38:39]
	v_mul_f32_e32 v41, v12, v18
	v_cvt_pk_bf16_f32 v41, v41, v129
	v_add_u32_e32 v3, 0x340000, v37
	global_store_short v3, v41, s[38:39]
	v_mul_f32_e32 v41, v19, v40
	v_cvt_pk_bf16_f32 v41, v41, v129
	v_add_u32_e32 v3, 0x280000, v37
	global_store_short v3, v41, s[38:39]
	v_mul_f32_e32 v41, v12, v19
	v_cvt_pk_bf16_f32 v41, v41, v129
	v_add_u32_e32 v3, 0x380000, v37
	global_store_short v3, v41, s[38:39]
	v_mul_f32_e32 v41, v20, v40
	v_cvt_pk_bf16_f32 v41, v41, v129
	v_add_u32_e32 v3, 0x2c0000, v37
	global_store_short v3, v41, s[38:39]
	v_mul_f32_e32 v41, v12, v20
	v_cvt_pk_bf16_f32 v41, v41, v129
	v_add_u32_e32 v3, 0x3c0000, v37
	global_store_short v3, v41, s[38:39]
	v_cmp_gt_u32_e32 vcc, 32, v2
	s_and_saveexec_b64 s[42:43], vcc
	v_mul_f32_e32 v41, v14, v9
	v_cvt_pk_bf16_f32 v41, v41, v129
	v_add_u32_e32 v3, 0x40000, v37
	global_store_short v3, v41, s[38:39]
	v_mul_f32_e32 v41, v10, v14
	v_cvt_pk_bf16_f32 v41, v41, v129
	v_add_u32_e32 v3, 0xa0000, v37
	global_store_short v3, v41, s[38:39]
	v_mul_f32_e32 v41, v16, v39
	v_cvt_pk_bf16_f32 v41, v41, v129
	v_add_u32_e32 v3, 0x140000, v37
	global_store_short v3, v41, s[38:39]
	v_mul_f32_e32 v41, v11, v16
	v_cvt_pk_bf16_f32 v41, v41, v129
	v_add_u32_e32 v3, 0x1a0000, v37
	global_store_short v3, v41, s[38:39]
	s_or_b64 exec, exec, s[42:43]
	v_add_u32_e32 v3, 0xc0000, v38
	global_store_short v3, v129, s[38:39]
	v_add_u32_e32 v3, 0x1c0000, v38
	global_store_short v3, v129, s[38:39]
	v_cvt_pk_bf16_f32 v41, v25, v129
	v_add_u32_e32 v3, 0x0, v38
	global_store_short v3, v41, s[72:73]
	v_cvt_pk_bf16_f32 v41, v26, v129
	v_add_u32_e32 v3, 0x40000, v38
	global_store_short v3, v41, s[72:73]
	v_cvt_pk_bf16_f32 v41, v27, v129
	v_add_u32_e32 v3, 0x80000, v38
	global_store_short v3, v41, s[72:73]
	v_cvt_pk_bf16_f32 v41, v28, v129
	v_add_u32_e32 v3, 0xc0000, v38
	global_store_short v3, v41, s[72:73]
	v_cvt_pk_bf16_f32 v41, v29, v129
	v_add_u32_e32 v3, 0x100000, v38
	global_store_short v3, v41, s[72:73]
	v_cvt_pk_bf16_f32 v41, v30, v129
	v_add_u32_e32 v3, 0x140000, v38
	global_store_short v3, v41, s[72:73]
	v_cvt_pk_bf16_f32 v41, v31, v129
	v_add_u32_e32 v3, 0x180000, v38
	global_store_short v3, v41, s[72:73]
	v_cvt_pk_bf16_f32 v41, v32, v129
	v_add_u32_e32 v3, 0x1c0000, v38
	global_store_short v3, v41, s[72:73]
	v_cvt_pk_bf16_f32 v41, v33, v129
	v_add_u32_e32 v3, 0x200000, v38
	global_store_short v3, v41, s[72:73]
	v_cvt_pk_bf16_f32 v41, v34, v129
	v_add_u32_e32 v3, 0x240000, v38
	global_store_short v3, v41, s[72:73]
	v_cvt_pk_bf16_f32 v41, v35, v129
	v_add_u32_e32 v3, 0x280000, v38
	global_store_short v3, v41, s[72:73]
	v_cvt_pk_bf16_f32 v41, v36, v129
	v_add_u32_e32 v3, 0x2c0000, v38
	global_store_short v3, v41, s[72:73]
	v_mov_b32_e32 v0, 0x7f000000
	s_branch .Lwp_join
.Lwp_orig:
	v_lshl_add_u32 v0, s23, 9, v43
.Lwp_join:
	s_mov_b32 s2, 0x30000
	v_cmp_gt_i32_e64 s[42:43], s2, v0
	s_and_saveexec_b64 s[12:13], s[42:43]
	s_mov_b32 s7, 0x2ffff
	s_mov_b32 s33, 0x1ffff
	s_cbranch_execz .LBB0_376
	s_load_dwordx2 s[18:19], s[64:65], 0x98
	s_waitcnt lgkmcnt(0)
	s_add_u32 s30, s8, 0x2000
	s_addc_u32 s31, s9, 0
	s_mov_b64 s[34:35], 0
	v_mov_b32_e32 v1, v0
